# RWKV scan waves at priority 1 (was 0)
# speedup vs baseline: 1.0043x; 1.0043x over previous
; #define LAUNDER_IDS const int tid__ = launder_v((int)threadIdx.x); const int blk__ = launder_s((int)blockIdx.x); (void)tid__; (void)blk__;
; DI void phase_scan(const Params& p, char* smem) {
;   LAUNDER_IDS
;   const int blk = blk__;
;   if (blk >= 256) return;
;   const int tid = tid__, lane = tid & 63, wave = tid >> 6, kq = lane & 15, rg = lane >> 4;
;   const int chain = (blk & 7) + 8 * (blk >> 5), quarter = (blk >> 3) & 3;
;   const int b = chain >> 3, h = (chain >> 1) & 3, dir = chain & 1;
;   const u16* sc = (const u16*)(p.ws + OFF_R3);
;   const size_t AS = (size_t)NT * 256;
;   const u16* aOMW = sc + (dir ? SA_OMWB : SA_OMWF) * AS;
;   const u16* aKD = sc + (dir ? SA_KDB : SA_KDF) * AS;
;   const u16* aB = sc + (dir ? SA_BB : SA_BF) * AS;
;   const u16* aKKN = sc + SA_KKN * AS;
;   const u16* aR = sc + SA_R * AS;
;   const u16* aV = sc + SA_V * AS;
;   u16* Y = (u16*)(p.ws + OFF_R2) + (dir ? AS : 0);
;   constexpr int CH = 16, BSZ = 5 * CH * 64 + CH * 16;
;   float* buf = (float*)smem;
;   const int st_ld = tid >> 4, k4 = (tid & 15) * 4;
;   const int vrow = quarter * 16 + wave * 4 + rg;
;   uint2 g0, g1, g2, g3, g4; u16 gv;
;     ...
;   float2_t S01 = {0.f, 0.f}, S23 = {0.f, 0.f};
;   __builtin_amdgcn_s_setprio(3);
;   __syncthreads();
;   SCAN_GLOAD(0); SCAN_LSTORE(0);
;   __syncthreads();
; __global__ void __launch_bounds__(256, 2) fwd_megakernel(Params pk) {
;     ...
;     switch (q) {
;       case 0: phase_norm(XLP, XCP, TABP(0), (u16*)(p.ws + OFF_HB1), NT); break;
;       case 1: phase_zgemm(p, l, smem); break;
;       case 2: phase_tokA(p, l); phase_tokB(p, l, smem); break;
;       case 3: phase_qkv(p, l, smem); break;
;       case 4: phase_scan(p, smem); phase_attn(p, l, smem); break;
.LBB0_497:
	s_and_b64 vcc, exec, s[4:5]
	s_cbranch_vccz .LBB0_958
	v_readlane_b32 s0, v253, 36
	s_cmp_gt_i32 s0, 1
	s_mov_b64 s[0:1], -1
	s_cbranch_scc0 .LBB0_848
	v_readlane_b32 s0, v253, 36
	s_cmp_lt_i32 s0, 3
	s_mov_b64 s[0:1], -1
	s_cbranch_scc1 .LBB0_754
	v_readlane_b32 s0, v253, 36
	s_cmp_gt_i32 s0, 3
	s_mov_b64 s[0:1], -1
	s_cbranch_scc0 .LBB0_542
	v_mov_b32_e32 v14, v163
	s_mov_b32 s6, s2
	s_cmpk_gt_i32 s6, 0xff
	s_cbranch_scc1 .LBB0_517
	s_ashr_i32 s8, s6, 5
	s_and_b32 s7, s6, 1
	s_cmp_eq_u32 s7, 0
	s_cselect_b64 s[0:1], -1, 0
	v_ashrrev_i32_e32 v3, 4, v14
	s_setprio 1
	s_movk_i32 s4, 0xff
	v_cmp_lt_i32_e32 vcc, s4, v3
	s_waitcnt lgkmcnt(0)
	s_barrier
	s_and_saveexec_b64 s[4:5], vcc
	s_xor_b64 s[4:5], exec, s[4:5]
	s_cbranch_execz .LBB0_504
	v_add_u32_e32 v0, 0xffffff00, v3
	v_sub_u32_e32 v2, 0x10ff, v3
	s_lshl_b32 s10, s8, 8
	s_lshl_b32 s9, s8, 12
	v_cndmask_b32_e64 v0, v2, v0, s[0:1]
	s_add_i32 s10, s10, 0x8000
	s_waitcnt vmcnt(0)
	v_add_u32_e32 v4, s9, v0
	v_mov_b32_e32 v22, s10
	v_mov_b32_e32 v23, s9
